# delta prep: Tinv tile transposed through the wave's dead LDS scratch and stored as 4 dwordx4 rows per lane instead of 32 two-byte stores
# speedup vs baseline: 1.0031x; 1.0006x over previous
; #define LAS __attribute__((address_space(3)))
; __device__ __forceinline__ void delta_prep_wave(const Params& P, LAS unsigned char* lds, int idx, int wave, int lane) {
;     ...
;     { int loff = hh * 1152;
;       float x[32];
; #pragma unroll
;       for (int i = 0; i < 32; ++i) { float sacc = (i == n) ? 1.f : 0.f;
;           const LAS float* Lb = Lm + loff;
; #pragma unroll
;           for (int j4 = 0; j4 < (i + 3) / 4; ++j4) { const f32x4 l = *(const LAS f32x4*)(Lb + i * 36 + 4 * j4);
; #pragma unroll
;               for (int jj = 0; jj < 4; ++jj) if (4 * j4 + jj < i) sacc -= l[jj] * x[4 * j4 + jj]; }
;           x[i] = sacc;
;           if ((i & 1) == 1) asm volatile("" : "+v"(loff) : "v"(sacc)); }
.LBB0_1107:
	s_movk_i32 s4, 0x480
	s_waitcnt lgkmcnt(0)
	v_mul_lo_u32 v1, v32, s4
	v_lshl_add_u32 v2, v1, 2, s3
	ds_read_b128 v[2:5], v2 offset:6288
	v_cmp_eq_u32_e32 vcc, 1, v152
	v_cndmask_b32_e64 v0, 0, 1.0, s[8:9]
	v_readlane_b32 s4, v238, 18
	v_cndmask_b32_e64 v6, 0, 1.0, vcc
	v_cmp_eq_u32_e32 vcc, 2, v152
	s_waitcnt lgkmcnt(0)
	v_fma_f32 v2, -v0, v2, v6
	v_readlane_b32 s5, v238, 19
	v_cndmask_b32_e64 v3, 0, 1.0, vcc
	v_cmp_eq_u32_e32 vcc, 3, v152
	v_lshl_add_u32 v8, v1, 2, s3
	ds_read_b128 v[4:7], v8 offset:6432
	v_cndmask_b32_e64 v10, 0, 1.0, vcc
	v_cmp_eq_u32_e32 vcc, 6, v152
	s_waitcnt lgkmcnt(0)
	ds_read_b128 v[6:9], v8 offset:6576
	v_lshlrev_b32_e32 v34, 1, v34
	v_cndmask_b32_e64 v20, 0, 1.0, vcc
	v_cmp_eq_u32_e32 vcc, 7, v152
	v_fma_f32 v3, -v0, v4, v3
	v_fma_f32 v3, -v5, v2, v3
	v_cndmask_b32_e64 v21, 0, 1.0, vcc
	v_cmp_eq_u32_e32 vcc, 8, v152
	s_waitcnt lgkmcnt(0)
	v_mov_b32_e32 v4, v7
	v_mov_b32_e32 v5, v8
	v_cndmask_b32_e64 v25, 0, 1.0, vcc
	v_cmp_eq_u32_e32 vcc, 9, v152
	v_fma_f32 v6, -v0, v6, v10
	v_pk_mul_f32 v[4:5], v[2:3], v[4:5]
	v_cndmask_b32_e64 v24, 0, 1.0, vcc
	v_cmp_eq_u32_e32 vcc, 10, v152
	v_sub_f32_e32 v4, v6, v4
	v_sub_f32_e32 v4, v4, v5
	v_cndmask_b32_e64 v50, 0, 1.0, vcc
	v_cmp_eq_u32_e32 vcc, 11, v152
	v_mov_b32_e32 v26, v3
	v_lshl_add_u32 v5, v1, 2, s3
	v_cndmask_b32_e64 v51, 0, 1.0, vcc
	v_cmp_eq_u32_e32 vcc, 12, v152
	ds_read_b128 v[6:9], v5 offset:6720
	ds_read_b128 v[10:13], v5 offset:6864
	v_cndmask_b32_e64 v23, 0, 1.0, vcc
	v_cmp_eq_u32_e32 vcc, 13, v152
	ds_read_b128 v[14:17], v5 offset:6880
	s_waitcnt lgkmcnt(0)
	v_mov_b32_e32 v17, v6
	v_cndmask_b32_e64 v22, 0, 1.0, vcc
	v_cmp_eq_u32_e32 vcc, 14, v152
	v_mov_b32_e32 v16, v10
	v_mov_b32_e32 v6, v11
	v_cndmask_b32_e64 v66, 0, 1.0, vcc
	v_cmp_eq_u32_e32 vcc, 15, v152
	v_mov_b32_e32 v10, v12
	v_mov_b32_e32 v11, v8
	v_cndmask_b32_e64 v67, 0, 1.0, vcc
	v_cmp_eq_u32_e32 vcc, 18, v152
	v_mov_b32_e32 v8, v13
	v_mov_b32_e32 v46, v3
	v_cndmask_b32_e64 v39, 0, 1.0, vcc
	v_cmp_eq_u32_e32 vcc, 19, v152
	v_mov_b32_e32 v47, v4
	s_cmpk_eq_i32 s78, 0x100
	v_cndmask_b32_e64 v37, 0, 1.0, vcc
	v_cmp_eq_u32_e32 vcc, 22, v152
	s_nop 1
	v_cndmask_b32_e64 v35, 0, 1.0, vcc
	v_cmp_eq_u32_e32 vcc, 23, v152
	s_nop 1
	v_cndmask_b32_e64 v33, 0, 1.0, vcc
	v_cmp_eq_u32_e32 vcc, 4, v152
	s_nop 1
	v_cndmask_b32_e64 v19, 0, 1.0, vcc
	v_cmp_eq_u32_e32 vcc, 5, v152
	s_nop 1
	v_cndmask_b32_e64 v18, 0, 1.0, vcc
	v_pk_fma_f32 v[16:17], v[0:1], v[16:17], v[18:19] op_sel_hi:[0,1,1] neg_lo:[1,0,0] neg_hi:[1,0,0]
	v_pk_fma_f32 v[6:7], v[2:3], v[6:7], v[16:17] op_sel_hi:[0,1,1] neg_lo:[1,0,0] neg_hi:[1,0,0]
	v_pk_fma_f32 v[6:7], v[26:27], v[10:11], v[6:7] op_sel_hi:[0,1,1] neg_lo:[1,0,0] neg_hi:[1,0,0]
	v_pk_fma_f32 v[6:7], v[8:9], v[4:5], v[6:7] op_sel_hi:[1,0,1] neg_lo:[1,0,0] neg_hi:[1,0,0]
	v_cmp_eq_u32_e32 vcc, 26, v152
	v_fma_f32 v9, -v14, v7, v6
	v_mov_b32_e32 v36, v9
	v_lshl_add_u32 v5, v1, 2, s3
	ds_read_b128 v[10:13], v5 offset:7008
	ds_read_b64 v[14:15], v5 offset:7024
	v_cndmask_b32_e64 v27, 0, 1.0, vcc
	v_cmp_eq_u32_e32 vcc, 16, v152
	s_waitcnt lgkmcnt(1)
	v_fma_f32 v8, -v0, v10, v20
	v_fma_f32 v8, -v2, v11, v8
	v_pk_mul_f32 v[10:11], v[46:47], v[12:13]
	v_cndmask_b32_e64 v41, 0, 1.0, vcc
	v_sub_f32_e32 v8, v8, v10
	v_sub_f32_e32 v16, v8, v11
	ds_read_b128 v[10:13], v5 offset:7152
	v_mov_b32_e32 v8, v7
	s_waitcnt lgkmcnt(1)
	v_pk_mul_f32 v[18:19], v[14:15], v[8:9]
	v_cmp_eq_u32_e32 vcc, 17, v152
	v_sub_f32_e32 v18, v16, v18
	ds_read_b128 v[14:17], v5 offset:7168
	s_waitcnt lgkmcnt(1)
	v_fma_f32 v5, -v0, v10, v21
	v_mov_b32_e32 v10, v11
	v_mov_b32_e32 v11, v12
	v_pk_mul_f32 v[10:11], v[2:3], v[10:11]
	v_cndmask_b32_e64 v40, 0, 1.0, vcc
	v_sub_f32_e32 v5, v5, v10
	v_sub_f32_e32 v12, v5, v11
	v_mov_b32_e32 v5, v7
	s_waitcnt lgkmcnt(0)
	v_pk_mov_b32 v[10:11], v[12:13], v[14:15] op_sel:[1,0]
	v_mov_b32_e32 v13, v16
	v_pk_mul_f32 v[10:11], v[4:5], v[10:11]
	v_cmp_eq_u32_e32 vcc, 20, v152
	v_sub_f32_e32 v10, v12, v10
	v_sub_f32_e32 v14, v10, v11
	v_sub_f32_e32 v11, v18, v19
	v_mov_b32_e32 v12, v15
	v_mov_b32_e32 v10, v9
	v_pk_mul_f32 v[12:13], v[12:13], v[10:11]
	v_mov_b32_e32 v38, v11
	v_sub_f32_e32 v12, v14, v12
	v_sub_f32_e32 v12, v12, v13
	s_nop 0
	v_lshl_add_u32 v13, v1, 2, s3
	ds_read_b128 v[14:17], v13 offset:7296
	ds_read_b128 v[18:21], v13 offset:7440
	ds_read_b128 v[28:31], v13 offset:7312
	ds_read_b128 v[42:45], v13 offset:7456
	s_waitcnt lgkmcnt(3)
	v_mov_b32_e32 v49, v14
	s_waitcnt lgkmcnt(2)
	v_mov_b32_e32 v48, v18
	v_pk_fma_f32 v[24:25], v[0:1], v[48:49], v[24:25] op_sel_hi:[0,1,1] neg_lo:[1,0,0] neg_hi:[1,0,0]
	v_mov_b32_e32 v14, v19
	v_pk_fma_f32 v[14:15], v[2:3], v[14:15], v[24:25] op_sel_hi:[0,1,1] neg_lo:[1,0,0] neg_hi:[1,0,0]
	v_mov_b32_e32 v18, v20
	v_mov_b32_e32 v19, v16
	v_pk_fma_f32 v[14:15], v[26:27], v[18:19], v[14:15] op_sel_hi:[0,1,1] neg_lo:[1,0,0] neg_hi:[1,0,0]
	v_mov_b32_e32 v16, v21
	v_pk_fma_f32 v[14:15], v[4:5], v[16:17], v[14:15] op_sel_hi:[0,1,1] neg_lo:[1,0,0] neg_hi:[1,0,0]
	s_waitcnt lgkmcnt(0)
	v_mov_b32_e32 v16, v42
	v_mov_b32_e32 v17, v28
	v_pk_fma_f32 v[14:15], v[6:7], v[16:17], v[14:15] op_sel:[1,0,0] neg_lo:[1,0,0] neg_hi:[1,0,0]
	ds_read_b128 v[16:19], v13 offset:7472
	v_mov_b32_e32 v28, v43
	v_pk_fma_f32 v[14:15], v[36:37], v[28:29], v[14:15] op_sel_hi:[0,1,1] neg_lo:[1,0,0] neg_hi:[1,0,0]
	v_mov_b32_e32 v20, v44
	v_mov_b32_e32 v21, v30
	v_pk_fma_f32 v[14:15], v[38:39], v[20:21], v[14:15] op_sel_hi:[0,1,1] neg_lo:[1,0,0] neg_hi:[1,0,0]
	v_mov_b32_e32 v30, v45
	v_pk_fma_f32 v[14:15], v[30:31], v[12:13], v[14:15] op_sel_hi:[1,0,1] neg_lo:[1,0,0] neg_hi:[1,0,0]
	v_cndmask_b32_e64 v49, 0, 1.0, vcc
	s_waitcnt lgkmcnt(0)
; #define LAS __attribute__((address_space(3)))
; __device__ __forceinline__ void delta_prep_wave(const Params& P, LAS unsigned char* lds, int idx, int wave, int lane) {
;     ...
;     { int loff = hh * 1152;
;       float x[32];
; #pragma unroll
;       for (int i = 0; i < 32; ++i) { float sacc = (i == n) ? 1.f : 0.f;
;           const LAS float* Lb = Lm + loff;
; #pragma unroll
;           for (int j4 = 0; j4 < (i + 3) / 4; ++j4) { const f32x4 l = *(const LAS f32x4*)(Lb + i * 36 + 4 * j4);
; #pragma unroll
;               for (int jj = 0; jj < 4; ++jj) if (4 * j4 + jj < i) sacc -= l[jj] * x[4 * j4 + jj]; }
;           x[i] = sacc;
;           if ((i & 1) == 1) asm volatile("" : "+v"(loff) : "v"(sacc)); }
	v_fma_f32 v17, -v16, v15, v14
	v_mov_b32_e32 v13, v15
	v_lshl_add_u32 v42, v1, 2, s3
	ds_read_b128 v[18:21], v42 offset:7584
	ds_read_b128 v[28:31], v42 offset:7600
	ds_read_b64 v[24:25], v42 offset:7616
	v_cmp_eq_u32_e32 vcc, 21, v152
	s_waitcnt lgkmcnt(2)
	v_fma_f32 v16, -v0, v18, v50
	v_fma_f32 v16, -v2, v19, v16
	v_pk_mul_f32 v[18:19], v[46:47], v[20:21]
	v_cndmask_b32_e64 v48, 0, 1.0, vcc
	v_sub_f32_e32 v16, v16, v18
	v_sub_f32_e32 v16, v16, v19
	s_waitcnt lgkmcnt(1)
	v_pk_mul_f32 v[18:19], v[8:9], v[28:29]
	v_cmp_eq_u32_e32 vcc, 27, v152
	v_sub_f32_e32 v8, v16, v18
	v_sub_f32_e32 v8, v8, v19
	v_mov_b32_e32 v18, v11
	v_mov_b32_e32 v19, v12
	v_pk_mul_f32 v[28:29], v[18:19], v[30:31]
	ds_read_b128 v[18:21], v42 offset:7728
	v_sub_f32_e32 v8, v8, v28
	v_sub_f32_e32 v8, v8, v29
	ds_read_b128 v[28:31], v42 offset:7744
	v_mov_b32_e32 v16, v15
	s_waitcnt lgkmcnt(2)
	v_pk_mul_f32 v[24:25], v[24:25], v[16:17]
	s_waitcnt lgkmcnt(1)
	v_fma_f32 v16, -v0, v18, v51
	v_mov_b32_e32 v18, v19
	v_mov_b32_e32 v19, v20
	v_pk_mul_f32 v[18:19], v[2:3], v[18:19]
	ds_read_b128 v[42:45], v42 offset:7760
	v_sub_f32_e32 v16, v16, v18
	v_sub_f32_e32 v16, v16, v19
	s_waitcnt lgkmcnt(1)
	v_pk_mov_b32 v[18:19], v[20:21], v[28:29] op_sel:[1,0]
	v_sub_f32_e32 v8, v8, v24
	v_pk_mul_f32 v[18:19], v[4:5], v[18:19]
	s_waitcnt lgkmcnt(0)
	v_mov_b32_e32 v20, v43
	v_sub_f32_e32 v16, v16, v18
	v_sub_f32_e32 v16, v16, v19
	v_mov_b32_e32 v18, v29
	v_mov_b32_e32 v19, v30
	v_pk_mul_f32 v[18:19], v[10:11], v[18:19]
	v_mov_b32_e32 v21, v44
	v_sub_f32_e32 v16, v16, v18
	v_sub_f32_e32 v16, v16, v19
	v_pk_mov_b32 v[18:19], v[30:31], v[42:43] op_sel:[1,0]
	s_nop 0
	v_pk_mul_f32 v[18:19], v[12:13], v[18:19]
	s_nop 0
	v_sub_f32_e32 v16, v16, v18
	v_sub_f32_e32 v16, v16, v19
	v_sub_f32_e32 v19, v8, v25
	v_mov_b32_e32 v18, v17
	v_pk_mul_f32 v[20:21], v[20:21], v[18:19]
	s_nop 0
	v_sub_f32_e32 v8, v16, v20
	v_sub_f32_e32 v20, v8, v21
	v_mov_b32_e32 v8, v17
	v_lshl_add_u32 v16, v1, 2, s3
	ds_read_b128 v[28:31], v16 offset:7904
	ds_read_b128 v[42:45], v16 offset:8016
	ds_read_b128 v[50:53], v16 offset:7872
	ds_read_b128 v[54:57], v16 offset:7888
	ds_read_b128 v[58:61], v16 offset:8032
	ds_read_b128 v[62:65], v16 offset:8048
	s_waitcnt lgkmcnt(4)
	v_mov_b32_e32 v24, v42
	s_waitcnt lgkmcnt(3)
	v_mov_b32_e32 v25, v50
	v_pk_fma_f32 v[22:23], v[0:1], v[24:25], v[22:23] op_sel_hi:[0,1,1] neg_lo:[1,0,0] neg_hi:[1,0,0]
	v_mov_b32_e32 v50, v43
	v_pk_fma_f32 v[22:23], v[2:3], v[50:51], v[22:23] op_sel_hi:[0,1,1] neg_lo:[1,0,0] neg_hi:[1,0,0]
	v_mov_b32_e32 v24, v44
	v_mov_b32_e32 v25, v52
	v_pk_fma_f32 v[22:23], v[26:27], v[24:25], v[22:23] op_sel_hi:[0,1,1] neg_lo:[1,0,0] neg_hi:[1,0,0]
	v_mov_b32_e32 v52, v45
	v_pk_fma_f32 v[22:23], v[4:5], v[52:53], v[22:23] op_sel_hi:[0,1,1] neg_lo:[1,0,0] neg_hi:[1,0,0]
	s_waitcnt lgkmcnt(1)
	v_mov_b32_e32 v24, v58
	v_mov_b32_e32 v25, v54
	v_pk_fma_f32 v[22:23], v[6:7], v[24:25], v[22:23] op_sel:[1,0,0] neg_lo:[1,0,0] neg_hi:[1,0,0]
	v_mov_b32_e32 v54, v59
	v_pk_fma_f32 v[22:23], v[36:37], v[54:55], v[22:23] op_sel_hi:[0,1,1] neg_lo:[1,0,0] neg_hi:[1,0,0]
	v_mov_b32_e32 v24, v60
	v_mov_b32_e32 v25, v56
	v_pk_fma_f32 v[22:23], v[38:39], v[24:25], v[22:23] op_sel_hi:[0,1,1] neg_lo:[1,0,0] neg_hi:[1,0,0]
	v_mov_b32_e32 v56, v61
	v_pk_fma_f32 v[22:23], v[12:13], v[56:57], v[22:23] op_sel_hi:[0,1,1] neg_lo:[1,0,0] neg_hi:[1,0,0]
	s_waitcnt lgkmcnt(0)
	v_mov_b32_e32 v24, v62
	v_mov_b32_e32 v25, v28
	ds_read_b128 v[42:45], v16 offset:8064
	v_pk_fma_f32 v[22:23], v[14:15], v[24:25], v[22:23] op_sel:[1,0,0] neg_lo:[1,0,0] neg_hi:[1,0,0]
	v_mov_b32_e32 v28, v63
	v_pk_fma_f32 v[22:23], v[8:9], v[28:29], v[22:23] op_sel_hi:[0,1,1] neg_lo:[1,0,0] neg_hi:[1,0,0]
	v_mov_b32_e32 v24, v64
	v_mov_b32_e32 v25, v30
	v_mov_b32_e32 v16, v19
	v_pk_fma_f32 v[22:23], v[16:17], v[24:25], v[22:23] op_sel_hi:[0,1,1] neg_lo:[1,0,0] neg_hi:[1,0,0]
	v_mov_b32_e32 v30, v65
	v_pk_fma_f32 v[22:23], v[30:31], v[20:21], v[22:23] op_sel_hi:[1,0,1] neg_lo:[1,0,0] neg_hi:[1,0,0]
	s_waitcnt lgkmcnt(0)
	v_fma_f32 v25, -v42, v23, v22
	v_mov_b32_e32 v21, v23
	v_lshl_add_u32 v54, v1, 2, s3
	ds_read_b128 v[28:31], v54 offset:8160
	ds_read_b128 v[42:45], v54 offset:8176
	ds_read_b128 v[50:53], v54 offset:8192
	ds_read_b64 v[46:47], v54 offset:8208
	s_waitcnt lgkmcnt(3)
	v_fma_f32 v24, -v0, v28, v66
	v_fma_f32 v24, -v2, v29, v24
	s_waitcnt lgkmcnt(2)
	v_pk_mov_b32 v[28:29], v[30:31], v[42:43] op_sel:[1,0]
	v_fma_f32 v24, -v3, v30, v24
	v_pk_mul_f32 v[28:29], v[4:5], v[28:29]
	s_nop 0
	v_sub_f32_e32 v24, v24, v28
	v_sub_f32_e32 v24, v24, v29
	v_mov_b32_e32 v28, v43
	v_mov_b32_e32 v29, v44
	v_pk_mul_f32 v[28:29], v[10:11], v[28:29]
	s_nop 0
	v_sub_f32_e32 v24, v24, v28
	v_sub_f32_e32 v24, v24, v29
	s_waitcnt lgkmcnt(1)
	v_pk_mov_b32 v[28:29], v[44:45], v[50:51] op_sel:[1,0]
	ds_read_b128 v[42:45], v54 offset:8320
	v_pk_mul_f32 v[28:29], v[12:13], v[28:29]
	s_nop 0
	v_sub_f32_e32 v24, v24, v28
	v_sub_f32_e32 v24, v24, v29
	v_mov_b32_e32 v28, v19
	v_mov_b32_e32 v29, v20
	v_fma_f32 v24, -v17, v51, v24
	v_pk_mul_f32 v[28:29], v[28:29], v[52:53]
	s_nop 0
	v_sub_f32_e32 v24, v24, v28
	v_sub_f32_e32 v50, v24, v29
	ds_read_b128 v[28:31], v54 offset:8304
	v_mov_b32_e32 v24, v23
	s_waitcnt lgkmcnt(2)
	v_pk_mul_f32 v[46:47], v[46:47], v[24:25]
	s_waitcnt lgkmcnt(0)
	v_fma_f32 v28, -v0, v28, v67
	v_fma_f32 v28, -v2, v29, v28
	v_fma_f32 v30, -v3, v30, v28
	v_pk_mov_b32 v[28:29], v[30:31], v[42:43] op_sel:[1,0]
	v_mov_b32_e32 v42, v43
	v_pk_mul_f32 v[28:29], v[4:5], v[28:29]
	v_mov_b32_e32 v43, v44
	v_sub_f32_e32 v5, v30, v28
	v_sub_f32_e32 v5, v5, v29
	ds_read_b128 v[28:31], v54 offset:8336
	v_pk_mul_f32 v[42:43], v[10:11], v[42:43]
	v_sub_f32_e32 v24, v50, v46
	v_sub_f32_e32 v5, v5, v42
	v_sub_f32_e32 v5, v5, v43
	ds_read_b128 v[50:53], v54 offset:8352
	s_waitcnt lgkmcnt(1)
; #define LAS __attribute__((address_space(3)))
; __device__ __forceinline__ void delta_prep_wave(const Params& P, LAS unsigned char* lds, int idx, int wave, int lane) {
;     ...
;     { int loff = hh * 1152;
;       float x[32];
; #pragma unroll
;       for (int i = 0; i < 32; ++i) { float sacc = (i == n) ? 1.f : 0.f;
;           const LAS float* Lb = Lm + loff;
; #pragma unroll
;           for (int j4 = 0; j4 < (i + 3) / 4; ++j4) { const f32x4 l = *(const LAS f32x4*)(Lb + i * 36 + 4 * j4);
; #pragma unroll
;               for (int jj = 0; jj < 4; ++jj) if (4 * j4 + jj < i) sacc -= l[jj] * x[4 * j4 + jj]; }
;           x[i] = sacc;
;           if ((i & 1) == 1) asm volatile("" : "+v"(loff) : "v"(sacc)); }
	v_pk_mov_b32 v[42:43], v[44:45], v[28:29] op_sel:[1,0]
	v_mov_b32_e32 v28, v29
	v_pk_mul_f32 v[42:43], v[12:13], v[42:43]
	v_mov_b32_e32 v29, v30
	v_sub_f32_e32 v5, v5, v42
	v_sub_f32_e32 v5, v5, v43
	v_pk_mul_f32 v[28:29], v[18:19], v[28:29]
	v_mov_b32_e32 v10, v25
	v_sub_f32_e32 v5, v5, v28
	v_sub_f32_e32 v5, v5, v29
	s_waitcnt lgkmcnt(0)
	v_pk_mov_b32 v[28:29], v[30:31], v[50:51] op_sel:[1,0]
	v_mov_b32_e32 v30, v51
	v_pk_mul_f32 v[28:29], v[20:21], v[28:29]
	v_mov_b32_e32 v31, v52
	v_sub_f32_e32 v5, v5, v28
	v_sub_f32_e32 v5, v5, v29
	v_sub_f32_e32 v29, v24, v47
	v_mov_b32_e32 v28, v25
	v_pk_mul_f32 v[30:31], v[30:31], v[28:29]
	v_mov_b32_e32 v24, v29
	v_sub_f32_e32 v5, v5, v30
	v_sub_f32_e32 v30, v5, v31
	s_nop 0
	v_lshl_add_u32 v5, v1, 2, s3
	ds_read_b128 v[42:45], v5 offset:8592
	ds_read_b128 v[50:53], v5 offset:8448
	ds_read_b128 v[54:57], v5 offset:8464
	ds_read_b128 v[58:61], v5 offset:8480
	ds_read_b128 v[62:65], v5 offset:8496
	ds_read_b128 v[66:69], v5 offset:8608
	s_waitcnt lgkmcnt(5)
	v_mov_b32_e32 v46, v42
	s_waitcnt lgkmcnt(4)
	v_mov_b32_e32 v47, v50
	v_pk_fma_f32 v[40:41], v[0:1], v[46:47], v[40:41] op_sel_hi:[0,1,1] neg_lo:[1,0,0] neg_hi:[1,0,0]
	v_mov_b32_e32 v50, v43
	v_pk_fma_f32 v[40:41], v[2:3], v[50:51], v[40:41] op_sel_hi:[0,1,1] neg_lo:[1,0,0] neg_hi:[1,0,0]
	v_mov_b32_e32 v42, v44
	v_mov_b32_e32 v43, v52
	v_pk_fma_f32 v[40:41], v[26:27], v[42:43], v[40:41] op_sel_hi:[0,1,1] neg_lo:[1,0,0] neg_hi:[1,0,0]
	v_mov_b32_e32 v52, v45
	v_pk_fma_f32 v[50:51], v[4:5], v[52:53], v[40:41] op_sel_hi:[0,1,1] neg_lo:[1,0,0] neg_hi:[1,0,0]
	s_waitcnt lgkmcnt(0)
	v_mov_b32_e32 v52, v66
	v_mov_b32_e32 v53, v54
	ds_read_b128 v[40:43], v5 offset:8624
	ds_read_b128 v[44:47], v5 offset:8640
	v_pk_fma_f32 v[50:51], v[6:7], v[52:53], v[50:51] op_sel:[1,0,0] neg_lo:[1,0,0] neg_hi:[1,0,0]
	v_mov_b32_e32 v54, v67
	v_pk_fma_f32 v[50:51], v[36:37], v[54:55], v[50:51] op_sel_hi:[0,1,1] neg_lo:[1,0,0] neg_hi:[1,0,0]
	v_mov_b32_e32 v52, v68
	v_mov_b32_e32 v53, v56
	v_pk_fma_f32 v[50:51], v[38:39], v[52:53], v[50:51] op_sel_hi:[0,1,1] neg_lo:[1,0,0] neg_hi:[1,0,0]
	v_mov_b32_e32 v56, v69
	v_pk_fma_f32 v[50:51], v[12:13], v[56:57], v[50:51] op_sel_hi:[0,1,1] neg_lo:[1,0,0] neg_hi:[1,0,0]
	s_waitcnt lgkmcnt(1)
	v_mov_b32_e32 v52, v40
	v_mov_b32_e32 v53, v58
	v_pk_fma_f32 v[50:51], v[14:15], v[52:53], v[50:51] op_sel:[1,0,0] neg_lo:[1,0,0] neg_hi:[1,0,0]
	v_mov_b32_e32 v58, v41
	v_pk_fma_f32 v[40:41], v[8:9], v[58:59], v[50:51] op_sel_hi:[0,1,1] neg_lo:[1,0,0] neg_hi:[1,0,0]
	v_mov_b32_e32 v50, v42
	v_mov_b32_e32 v51, v60
	v_pk_fma_f32 v[40:41], v[16:17], v[50:51], v[40:41] op_sel_hi:[0,1,1] neg_lo:[1,0,0] neg_hi:[1,0,0]
	v_mov_b32_e32 v60, v43
	v_pk_fma_f32 v[40:41], v[20:21], v[60:61], v[40:41] op_sel_hi:[0,1,1] neg_lo:[1,0,0] neg_hi:[1,0,0]
	s_waitcnt lgkmcnt(0)
	v_mov_b32_e32 v42, v44
	v_mov_b32_e32 v43, v62
	v_pk_fma_f32 v[40:41], v[22:23], v[42:43], v[40:41] op_sel:[1,0,0] neg_lo:[1,0,0] neg_hi:[1,0,0]
	v_mov_b32_e32 v62, v45
	ds_read_b128 v[42:45], v5 offset:8656
	v_pk_fma_f32 v[40:41], v[10:11], v[62:63], v[40:41] op_sel_hi:[0,1,1] neg_lo:[1,0,0] neg_hi:[1,0,0]
	v_mov_b32_e32 v50, v46
	v_mov_b32_e32 v51, v64
	v_pk_fma_f32 v[40:41], v[24:25], v[50:51], v[40:41] op_sel_hi:[0,1,1] neg_lo:[1,0,0] neg_hi:[1,0,0]
	v_mov_b32_e32 v64, v47
	v_pk_fma_f32 v[40:41], v[64:65], v[30:31], v[40:41] op_sel_hi:[1,0,1] neg_lo:[1,0,0] neg_hi:[1,0,0]
	s_waitcnt lgkmcnt(0)
	v_fma_f32 v43, -v42, v41, v40
	v_mov_b32_e32 v42, v41
	v_lshl_add_u32 v5, v1, 2, s3
	ds_read_b128 v[44:47], v5 offset:8736
	ds_read_b128 v[50:53], v5 offset:8752
	ds_read_b128 v[54:57], v5 offset:8768
	ds_read_b128 v[58:61], v5 offset:8784
	v_mov_b32_e32 v31, v41
	s_waitcnt lgkmcnt(3)
	v_fma_f32 v39, -v0, v44, v39
	v_fma_f32 v39, -v2, v45, v39
	v_fma_f32 v39, -v3, v46, v39
	v_fma_f32 v39, -v4, v47, v39
	s_waitcnt lgkmcnt(2)
	v_fma_f32 v39, -v7, v50, v39
	v_fma_f32 v39, -v9, v51, v39
	s_waitcnt lgkmcnt(1)
	v_pk_mov_b32 v[44:45], v[52:53], v[54:55] op_sel:[1,0]
	v_fma_f32 v39, -v11, v52, v39
	v_pk_mul_f32 v[44:45], v[12:13], v[44:45]
	ds_read_b64 v[52:53], v5 offset:8800
	v_sub_f32_e32 v39, v39, v44
	v_sub_f32_e32 v39, v39, v45
	v_mov_b32_e32 v44, v55
	v_mov_b32_e32 v45, v56
	v_pk_mul_f32 v[44:45], v[18:19], v[44:45]
	s_nop 0
	v_sub_f32_e32 v39, v39, v44
	v_sub_f32_e32 v39, v39, v45
	s_waitcnt lgkmcnt(1)
	v_pk_mov_b32 v[44:45], v[56:57], v[58:59] op_sel:[1,0]
	ds_read_b128 v[54:57], v5 offset:8912
	v_pk_mul_f32 v[44:45], v[20:21], v[44:45]
	s_nop 0
	v_sub_f32_e32 v39, v39, v44
	v_sub_f32_e32 v39, v39, v45
	v_mov_b32_e32 v44, v29
	v_mov_b32_e32 v45, v30
	v_pk_mul_f32 v[50:51], v[44:45], v[60:61]
	ds_read_b128 v[44:47], v5 offset:8880
	v_fma_f32 v39, -v25, v59, v39
	v_sub_f32_e32 v39, v39, v50
	v_sub_f32_e32 v39, v39, v51
	s_waitcnt lgkmcnt(2)
	v_pk_mul_f32 v[58:59], v[52:53], v[42:43]
	ds_read_b128 v[50:53], v5 offset:8896
	s_waitcnt lgkmcnt(1)
	v_fma_f32 v37, -v0, v44, v37
	v_fma_f32 v37, -v2, v45, v37
	v_fma_f32 v37, -v3, v46, v37
	v_fma_f32 v37, -v4, v47, v37
	s_waitcnt lgkmcnt(0)
	v_fma_f32 v37, -v7, v50, v37
	v_fma_f32 v37, -v9, v51, v37
	v_pk_mov_b32 v[44:45], v[52:53], v[54:55] op_sel:[1,0]
	v_fma_f32 v37, -v11, v52, v37
	v_pk_mul_f32 v[44:45], v[12:13], v[44:45]
	v_mov_b32_e32 v50, v55
	v_sub_f32_e32 v13, v37, v44
	v_sub_f32_e32 v13, v13, v45
	ds_read_b128 v[44:47], v5 offset:8928
	v_mov_b32_e32 v51, v56
	v_pk_mul_f32 v[50:51], v[18:19], v[50:51]
	v_sub_f32_e32 v39, v39, v58
	v_sub_f32_e32 v13, v13, v50
	v_sub_f32_e32 v13, v13, v51
	ds_read_b128 v[50:53], v5 offset:8944
	s_waitcnt lgkmcnt(1)
; #define LAS __attribute__((address_space(3)))
; __device__ __forceinline__ void delta_prep_wave(const Params& P, LAS unsigned char* lds, int idx, int wave, int lane) {
;     ...
;     { int loff = hh * 1152;
;       float x[32];
; #pragma unroll
;       for (int i = 0; i < 32; ++i) { float sacc = (i == n) ? 1.f : 0.f;
;           const LAS float* Lb = Lm + loff;
; #pragma unroll
;           for (int j4 = 0; j4 < (i + 3) / 4; ++j4) { const f32x4 l = *(const LAS f32x4*)(Lb + i * 36 + 4 * j4);
; #pragma unroll
;               for (int jj = 0; jj < 4; ++jj) if (4 * j4 + jj < i) sacc -= l[jj] * x[4 * j4 + jj]; }
;           x[i] = sacc;
;           if ((i & 1) == 1) asm volatile("" : "+v"(loff) : "v"(sacc)); }
	v_pk_mov_b32 v[54:55], v[56:57], v[44:45] op_sel:[1,0]
	v_mov_b32_e32 v44, v45
	v_pk_mul_f32 v[54:55], v[20:21], v[54:55]
	v_mov_b32_e32 v45, v46
	v_sub_f32_e32 v5, v13, v54
	v_sub_f32_e32 v5, v5, v55
	v_pk_mul_f32 v[44:45], v[28:29], v[44:45]
	v_mov_b32_e32 v18, v43
	v_sub_f32_e32 v5, v5, v44
	v_sub_f32_e32 v5, v5, v45
	s_waitcnt lgkmcnt(0)
	v_pk_mov_b32 v[44:45], v[46:47], v[50:51] op_sel:[1,0]
	v_mov_b32_e32 v46, v51
	v_pk_mul_f32 v[44:45], v[30:31], v[44:45]
	v_mov_b32_e32 v47, v52
	v_sub_f32_e32 v5, v5, v44
	v_sub_f32_e32 v5, v5, v45
	v_sub_f32_e32 v45, v39, v59
	v_mov_b32_e32 v44, v43
	v_pk_mul_f32 v[46:47], v[46:47], v[44:45]
	v_mov_b32_e32 v42, v45
	v_sub_f32_e32 v5, v5, v46
	v_sub_f32_e32 v46, v5, v47
	s_nop 0
	v_lshl_add_u32 v5, v1, 2, s3
	ds_read_b128 v[50:53], v5 offset:9088
	ds_read_b128 v[54:57], v5 offset:9168
	ds_read_b128 v[58:61], v5 offset:9024
	ds_read_b128 v[62:65], v5 offset:9040
	ds_read_b128 v[66:69], v5 offset:9056
	ds_read_b128 v[70:73], v5 offset:9072
	ds_read_b128 v[74:77], v5 offset:9184
	s_waitcnt lgkmcnt(5)
	v_mov_b32_e32 v78, v54
	s_waitcnt lgkmcnt(4)
	v_mov_b32_e32 v79, v58
	v_pk_fma_f32 v[48:49], v[0:1], v[78:79], v[48:49] op_sel_hi:[0,1,1] neg_lo:[1,0,0] neg_hi:[1,0,0]
	v_mov_b32_e32 v58, v55
	v_pk_fma_f32 v[48:49], v[2:3], v[58:59], v[48:49] op_sel_hi:[0,1,1] neg_lo:[1,0,0] neg_hi:[1,0,0]
	v_mov_b32_e32 v54, v56
	v_mov_b32_e32 v55, v60
	v_pk_fma_f32 v[48:49], v[26:27], v[54:55], v[48:49] op_sel_hi:[0,1,1] neg_lo:[1,0,0] neg_hi:[1,0,0]
	v_mov_b32_e32 v60, v57
	ds_read_b128 v[54:57], v5 offset:9200
	v_pk_fma_f32 v[48:49], v[4:5], v[60:61], v[48:49] op_sel_hi:[0,1,1] neg_lo:[1,0,0] neg_hi:[1,0,0]
	s_waitcnt lgkmcnt(1)
	v_mov_b32_e32 v58, v74
	v_mov_b32_e32 v59, v62
	v_pk_fma_f32 v[48:49], v[6:7], v[58:59], v[48:49] op_sel:[1,0,0] neg_lo:[1,0,0] neg_hi:[1,0,0]
	v_mov_b32_e32 v62, v75
	v_pk_fma_f32 v[48:49], v[36:37], v[62:63], v[48:49] op_sel_hi:[0,1,1] neg_lo:[1,0,0] neg_hi:[1,0,0]
	v_mov_b32_e32 v58, v76
	v_mov_b32_e32 v59, v64
	v_pk_fma_f32 v[48:49], v[38:39], v[58:59], v[48:49] op_sel_hi:[0,1,1] neg_lo:[1,0,0] neg_hi:[1,0,0]
	v_mov_b32_e32 v64, v77
	v_pk_fma_f32 v[48:49], v[12:13], v[64:65], v[48:49] op_sel_hi:[0,1,1] neg_lo:[1,0,0] neg_hi:[1,0,0]
	s_waitcnt lgkmcnt(0)
	v_mov_b32_e32 v78, v54
	v_mov_b32_e32 v79, v66
	ds_read_b128 v[58:61], v5 offset:9216
	ds_read_b128 v[62:65], v5 offset:9232
	ds_read_b128 v[74:77], v5 offset:9248
	v_pk_fma_f32 v[48:49], v[14:15], v[78:79], v[48:49] op_sel:[1,0,0] neg_lo:[1,0,0] neg_hi:[1,0,0]
	v_mov_b32_e32 v66, v55
	v_pk_fma_f32 v[48:49], v[8:9], v[66:67], v[48:49] op_sel_hi:[0,1,1] neg_lo:[1,0,0] neg_hi:[1,0,0]
	v_mov_b32_e32 v54, v56
	v_mov_b32_e32 v55, v68
	v_pk_fma_f32 v[48:49], v[16:17], v[54:55], v[48:49] op_sel_hi:[0,1,1] neg_lo:[1,0,0] neg_hi:[1,0,0]
	v_mov_b32_e32 v68, v57
	v_pk_fma_f32 v[48:49], v[20:21], v[68:69], v[48:49] op_sel_hi:[0,1,1] neg_lo:[1,0,0] neg_hi:[1,0,0]
	s_waitcnt lgkmcnt(2)
	v_mov_b32_e32 v54, v58
	v_mov_b32_e32 v55, v70
	v_pk_fma_f32 v[48:49], v[22:23], v[54:55], v[48:49] op_sel:[1,0,0] neg_lo:[1,0,0] neg_hi:[1,0,0]
	v_mov_b32_e32 v70, v59
	v_pk_fma_f32 v[48:49], v[10:11], v[70:71], v[48:49] op_sel_hi:[0,1,1] neg_lo:[1,0,0] neg_hi:[1,0,0]
	v_mov_b32_e32 v54, v60
	v_mov_b32_e32 v55, v72
	v_pk_fma_f32 v[48:49], v[24:25], v[54:55], v[48:49] op_sel_hi:[0,1,1] neg_lo:[1,0,0] neg_hi:[1,0,0]
	v_mov_b32_e32 v72, v61
	v_pk_fma_f32 v[48:49], v[30:31], v[72:73], v[48:49] op_sel_hi:[0,1,1] neg_lo:[1,0,0] neg_hi:[1,0,0]
	s_waitcnt lgkmcnt(1)
	v_mov_b32_e32 v54, v62
	v_mov_b32_e32 v55, v50
	v_pk_fma_f32 v[48:49], v[40:41], v[54:55], v[48:49] op_sel:[1,0,0] neg_lo:[1,0,0] neg_hi:[1,0,0]
	v_mov_b32_e32 v50, v63
	v_pk_fma_f32 v[48:49], v[18:19], v[50:51], v[48:49] op_sel_hi:[0,1,1] neg_lo:[1,0,0] neg_hi:[1,0,0]
	v_mov_b32_e32 v50, v64
	v_mov_b32_e32 v51, v52
	v_pk_fma_f32 v[48:49], v[42:43], v[50:51], v[48:49] op_sel_hi:[0,1,1] neg_lo:[1,0,0] neg_hi:[1,0,0]
	v_mov_b32_e32 v52, v65
	v_pk_fma_f32 v[48:49], v[52:53], v[46:47], v[48:49] op_sel_hi:[1,0,1] neg_lo:[1,0,0] neg_hi:[1,0,0]
	v_cndmask_b32_e64 v13, 0, 1.0, vcc
	s_waitcnt lgkmcnt(0)
	v_fma_f32 v51, -v74, v49, v48
	v_mov_b32_e32 v50, v49
	v_lshl_add_u32 v5, v1, 2, s3
	ds_read_b128 v[52:55], v5 offset:9312
	ds_read_b128 v[56:59], v5 offset:9328
	ds_read_b128 v[60:63], v5 offset:9344
	ds_read_b128 v[64:67], v5 offset:9360
	v_mov_b32_e32 v47, v49
	v_cmp_eq_u32_e32 vcc, 24, v152
	s_waitcnt lgkmcnt(3)
	v_fma_f32 v35, -v0, v52, v35
	v_fma_f32 v35, -v2, v53, v35
	v_fma_f32 v35, -v3, v54, v35
	v_fma_f32 v35, -v4, v55, v35
	s_waitcnt lgkmcnt(2)
	v_fma_f32 v35, -v7, v56, v35
	v_fma_f32 v35, -v9, v57, v35
	v_fma_f32 v35, -v11, v58, v35
	v_fma_f32 v35, -v12, v59, v35
	s_waitcnt lgkmcnt(1)
	v_fma_f32 v35, -v15, v60, v35
	v_fma_f32 v35, -v17, v61, v35
	s_waitcnt lgkmcnt(0)
	v_pk_mov_b32 v[52:53], v[62:63], v[64:65] op_sel:[1,0]
	v_fma_f32 v35, -v19, v62, v35
	v_pk_mul_f32 v[52:53], v[20:21], v[52:53]
	v_mov_b32_e32 v56, v65
	v_sub_f32_e32 v35, v35, v52
	v_sub_f32_e32 v35, v35, v53
	ds_read_b128 v[52:55], v5 offset:9376
	ds_read_b64 v[58:59], v5 offset:9392
	v_mov_b32_e32 v57, v66
	v_pk_mul_f32 v[56:57], v[28:29], v[56:57]
	ds_read_b128 v[62:65], v5 offset:9504
	v_sub_f32_e32 v35, v35, v56
	v_sub_f32_e32 v35, v35, v57
	s_waitcnt lgkmcnt(2)
	v_pk_mov_b32 v[56:57], v[66:67], v[52:53] op_sel:[1,0]
	s_waitcnt lgkmcnt(1)
	v_pk_mul_f32 v[66:67], v[58:59], v[50:51]
	v_pk_mul_f32 v[56:57], v[30:31], v[56:57]
	ds_read_b128 v[58:61], v5 offset:9472
	v_sub_f32_e32 v35, v35, v56
	v_sub_f32_e32 v35, v35, v57
	v_mov_b32_e32 v56, v45
	v_mov_b32_e32 v57, v46
	v_fma_f32 v35, -v43, v53, v35
	v_pk_mul_f32 v[52:53], v[56:57], v[54:55]
	v_cndmask_b32_e64 v91, 0, 1.0, vcc
	v_sub_f32_e32 v35, v35, v52
	v_sub_f32_e32 v35, v35, v53
	ds_read_b128 v[52:55], v5 offset:9456
	v_sub_f32_e32 v35, v35, v66
	v_cmp_eq_u32_e32 vcc, 25, v152
	s_waitcnt lgkmcnt(0)
; #define LAS __attribute__((address_space(3)))
; __device__ __forceinline__ int perm16(int e) { return (e & ~12) | ((e >> 1) & 4) | ((e << 1) & 8); }
; __device__ __forceinline__ void delta_prep_wave(const Params& P, LAS unsigned char* lds, int idx, int wave, int lane) {
;     ...
;     { int loff = hh * 1152;
;       float x[32];
; #pragma unroll
;       for (int i = 0; i < 32; ++i) { float sacc = (i == n) ? 1.f : 0.f;
;           const LAS float* Lb = Lm + loff;
; #pragma unroll
;           for (int j4 = 0; j4 < (i + 3) / 4; ++j4) { const f32x4 l = *(const LAS f32x4*)(Lb + i * 36 + 4 * j4);
; #pragma unroll
;               for (int jj = 0; jj < 4; ++jj) if (4 * j4 + jj < i) sacc -= l[jj] * x[4 * j4 + jj]; }
;           x[i] = sacc;
;           if ((i & 1) == 1) asm volatile("" : "+v"(loff) : "v"(sacc)); }
;       bf16* ti = TINV + ((size_t)bh * 64 + span * 2 + hh) * 1024 + perm16(n);
	v_fma_f32 v33, -v0, v52, v33
	v_fma_f32 v33, -v2, v53, v33
	v_fma_f32 v33, -v3, v54, v33
	v_fma_f32 v33, -v4, v55, v33
	ds_read_b128 v[52:55], v5 offset:9488
	v_fma_f32 v33, -v7, v58, v33
	v_fma_f32 v33, -v9, v59, v33
	v_fma_f32 v33, -v11, v60, v33
	v_fma_f32 v33, -v12, v61, v33
	s_waitcnt lgkmcnt(0)
	v_fma_f32 v33, -v15, v52, v33
	v_fma_f32 v33, -v17, v53, v33
	v_pk_mov_b32 v[52:53], v[54:55], v[62:63] op_sel:[1,0]
	v_fma_f32 v33, -v19, v54, v33
	v_pk_mul_f32 v[52:53], v[20:21], v[52:53]
	v_mov_b32_e32 v58, v63
	v_sub_f32_e32 v21, v33, v52
	v_sub_f32_e32 v21, v21, v53
	ds_read_b128 v[52:55], v5 offset:9520
	v_mov_b32_e32 v59, v64
	v_pk_mul_f32 v[58:59], v[28:29], v[58:59]
	v_cndmask_b32_e64 v90, 0, 1.0, vcc
	v_sub_f32_e32 v21, v21, v58
	v_sub_f32_e32 v21, v21, v59
	ds_read_b128 v[58:61], v5 offset:9536
	s_waitcnt lgkmcnt(1)
	v_pk_mov_b32 v[62:63], v[64:65], v[52:53] op_sel:[1,0]
	v_mov_b32_e32 v52, v53
	v_pk_mul_f32 v[62:63], v[30:31], v[62:63]
	v_mov_b32_e32 v53, v54
	v_sub_f32_e32 v5, v21, v62
	v_sub_f32_e32 v5, v5, v63
	v_pk_mul_f32 v[52:53], v[44:45], v[52:53]
	v_cmp_eq_u32_e32 vcc, 30, v152
	v_sub_f32_e32 v5, v5, v52
	v_sub_f32_e32 v5, v5, v53
	s_waitcnt lgkmcnt(0)
	v_pk_mov_b32 v[52:53], v[54:55], v[58:59] op_sel:[1,0]
	v_mov_b32_e32 v54, v59
	v_pk_mul_f32 v[52:53], v[46:47], v[52:53]
	v_mov_b32_e32 v55, v60
	v_sub_f32_e32 v5, v5, v52
	v_sub_f32_e32 v5, v5, v53
	v_sub_f32_e32 v53, v35, v67
	v_mov_b32_e32 v52, v51
	v_pk_mul_f32 v[54:55], v[54:55], v[52:53]
	v_ashrrev_i32_e32 v33, 31, v32
	v_sub_f32_e32 v5, v5, v54
	v_sub_f32_e32 v54, v5, v55
	v_lshl_add_u64 v[32:33], s[6:7], 0, v[32:33]
	v_lshl_add_u32 v5, v1, 2, s3
	ds_read_b128 v[58:61], v5 offset:9600
	ds_read_b128 v[62:65], v5 offset:9616
	ds_read_b128 v[66:69], v5 offset:9632
	ds_read_b128 v[70:73], v5 offset:9648
	ds_read_b128 v[74:77], v5 offset:9664
	ds_read_b128 v[78:81], v5 offset:9680
	ds_read_b128 v[82:85], v5 offset:9744
	ds_read_b128 v[86:89], v5 offset:9760
	s_waitcnt lgkmcnt(7)
	v_mov_b32_e32 v93, v58
	v_lshlrev_b64 v[32:33], 11, v[32:33]
	v_lshl_add_u64 v[32:33], s[4:5], 0, v[32:33]
	s_waitcnt lgkmcnt(1)
	v_mov_b32_e32 v92, v82
	v_pk_fma_f32 v[94:95], v[0:1], v[92:93], v[90:91] op_sel_hi:[0,1,1] neg_lo:[1,0,0] neg_hi:[1,0,0]
	v_mov_b32_e32 v58, v83
	v_pk_fma_f32 v[58:59], v[2:3], v[58:59], v[94:95] op_sel_hi:[0,1,1] neg_lo:[1,0,0] neg_hi:[1,0,0]
	v_mov_b32_e32 v82, v84
	v_mov_b32_e32 v83, v60
	v_pk_fma_f32 v[58:59], v[26:27], v[82:83], v[58:59] op_sel_hi:[0,1,1] neg_lo:[1,0,0] neg_hi:[1,0,0]
	v_mov_b32_e32 v60, v85
	ds_read_b128 v[90:93], v5 offset:9776
	v_pk_fma_f32 v[58:59], v[4:5], v[60:61], v[58:59] op_sel_hi:[0,1,1] neg_lo:[1,0,0] neg_hi:[1,0,0]
	s_waitcnt lgkmcnt(1)
	v_mov_b32_e32 v60, v86
	v_mov_b32_e32 v61, v62
	v_pk_fma_f32 v[58:59], v[6:7], v[60:61], v[58:59] op_sel:[1,0,0] neg_lo:[1,0,0] neg_hi:[1,0,0]
	v_mov_b32_e32 v62, v87
	v_pk_fma_f32 v[58:59], v[36:37], v[62:63], v[58:59] op_sel_hi:[0,1,1] neg_lo:[1,0,0] neg_hi:[1,0,0]
	v_mov_b32_e32 v60, v88
	v_mov_b32_e32 v61, v64
	v_pk_fma_f32 v[58:59], v[38:39], v[60:61], v[58:59] op_sel_hi:[0,1,1] neg_lo:[1,0,0] neg_hi:[1,0,0]
	v_mov_b32_e32 v64, v89
	v_pk_fma_f32 v[62:63], v[12:13], v[64:65], v[58:59] op_sel_hi:[0,1,1] neg_lo:[1,0,0] neg_hi:[1,0,0]
	ds_read_b128 v[58:61], v5 offset:9792
	s_waitcnt lgkmcnt(1)
	v_mov_b32_e32 v64, v90
	v_mov_b32_e32 v65, v66
	v_pk_fma_f32 v[62:63], v[14:15], v[64:65], v[62:63] op_sel:[1,0,0] neg_lo:[1,0,0] neg_hi:[1,0,0]
	v_mov_b32_e32 v66, v91
	v_pk_fma_f32 v[62:63], v[8:9], v[66:67], v[62:63] op_sel_hi:[0,1,1] neg_lo:[1,0,0] neg_hi:[1,0,0]
	v_mov_b32_e32 v64, v92
	v_mov_b32_e32 v65, v68
	v_pk_fma_f32 v[62:63], v[16:17], v[64:65], v[62:63] op_sel_hi:[0,1,1] neg_lo:[1,0,0] neg_hi:[1,0,0]
	v_mov_b32_e32 v68, v93
	v_pk_fma_f32 v[86:87], v[20:21], v[68:69], v[62:63] op_sel_hi:[0,1,1] neg_lo:[1,0,0] neg_hi:[1,0,0]
	s_waitcnt lgkmcnt(0)
	v_mov_b32_e32 v88, v58
	v_mov_b32_e32 v89, v70
	ds_read_b128 v[62:65], v5 offset:9808
	ds_read_b128 v[66:69], v5 offset:9824
	ds_read_b128 v[82:85], v5 offset:9840
	s_waitcnt lgkmcnt(0)
	v_pk_fma_f32 v[84:85], v[22:23], v[88:89], v[86:87] op_sel:[1,0,0] neg_lo:[1,0,0] neg_hi:[1,0,0]
	v_mov_b32_e32 v70, v59
	v_pk_fma_f32 v[58:59], v[10:11], v[70:71], v[84:85] op_sel_hi:[0,1,1] neg_lo:[1,0,0] neg_hi:[1,0,0]
	v_mov_b32_e32 v70, v60
	v_mov_b32_e32 v71, v72
	v_pk_fma_f32 v[58:59], v[24:25], v[70:71], v[58:59] op_sel_hi:[0,1,1] neg_lo:[1,0,0] neg_hi:[1,0,0]
	v_mov_b32_e32 v72, v61
	v_pk_fma_f32 v[58:59], v[30:31], v[72:73], v[58:59] op_sel_hi:[0,1,1] neg_lo:[1,0,0] neg_hi:[1,0,0]
	v_mov_b32_e32 v60, v62
	v_mov_b32_e32 v61, v74
	v_pk_fma_f32 v[58:59], v[40:41], v[60:61], v[58:59] op_sel:[1,0,0] neg_lo:[1,0,0] neg_hi:[1,0,0]
	v_mov_b32_e32 v74, v63
	v_pk_fma_f32 v[58:59], v[18:19], v[74:75], v[58:59] op_sel_hi:[0,1,1] neg_lo:[1,0,0] neg_hi:[1,0,0]
	v_mov_b32_e32 v60, v64
	v_mov_b32_e32 v61, v76
	v_pk_fma_f32 v[58:59], v[42:43], v[60:61], v[58:59] op_sel_hi:[0,1,1] neg_lo:[1,0,0] neg_hi:[1,0,0]
	v_mov_b32_e32 v76, v65
	v_pk_fma_f32 v[58:59], v[46:47], v[76:77], v[58:59] op_sel_hi:[0,1,1] neg_lo:[1,0,0] neg_hi:[1,0,0]
	v_mov_b32_e32 v60, v66
	v_mov_b32_e32 v61, v78
	v_pk_fma_f32 v[58:59], v[48:49], v[60:61], v[58:59] op_sel:[1,0,0] neg_lo:[1,0,0] neg_hi:[1,0,0]
	v_mov_b32_e32 v78, v67
	v_mov_b32_e32 v66, v51
	v_pk_fma_f32 v[58:59], v[66:67], v[78:79], v[58:59] op_sel_hi:[0,1,1] neg_lo:[1,0,0] neg_hi:[1,0,0]
	v_mov_b32_e32 v60, v68
	v_mov_b32_e32 v61, v80
	v_mov_b32_e32 v68, v53
	v_pk_fma_f32 v[58:59], v[68:69], v[60:61], v[58:59] op_sel_hi:[0,1,1] neg_lo:[1,0,0] neg_hi:[1,0,0]
	v_mov_b32_e32 v80, v69
	v_pk_fma_f32 v[58:59], v[80:81], v[54:55], v[58:59] op_sel_hi:[1,0,1] neg_lo:[1,0,0] neg_hi:[1,0,0]
	v_cndmask_b32_e64 v21, 0, 1.0, vcc
	v_fma_f32 v61, -v82, v59, v58
	v_mov_b32_e32 v60, v59
	v_lshl_add_u32 v5, v1, 2, s3
	ds_read_b128 v[62:65], v5 offset:9888
	ds_read_b128 v[70:73], v5 offset:9904
	ds_read_b128 v[74:77], v5 offset:9920
	ds_read_b128 v[78:81], v5 offset:9936
	v_mov_b32_e32 v55, v59
	v_cmp_eq_u32_e32 vcc, 28, v152
	v_mov_b32_e32 v35, 0
	s_waitcnt lgkmcnt(3)
; #define LAS __attribute__((address_space(3)))
; __device__ __forceinline__ void delta_prep_wave(const Params& P, LAS unsigned char* lds, int idx, int wave, int lane) {
;     ...
;     { int loff = hh * 1152;
;       float x[32];
; #pragma unroll
;       for (int i = 0; i < 32; ++i) { float sacc = (i == n) ? 1.f : 0.f;
;           const LAS float* Lb = Lm + loff;
; #pragma unroll
;           for (int j4 = 0; j4 < (i + 3) / 4; ++j4) { const f32x4 l = *(const LAS f32x4*)(Lb + i * 36 + 4 * j4);
; #pragma unroll
;               for (int jj = 0; jj < 4; ++jj) if (4 * j4 + jj < i) sacc -= l[jj] * x[4 * j4 + jj]; }
;           x[i] = sacc;
;           if ((i & 1) == 1) asm volatile("" : "+v"(loff) : "v"(sacc)); }
	v_fma_f32 v27, -v0, v62, v27
	v_fma_f32 v27, -v2, v63, v27
	v_fma_f32 v27, -v3, v64, v27
	v_fma_f32 v27, -v4, v65, v27
	s_waitcnt lgkmcnt(2)
	v_fma_f32 v27, -v7, v70, v27
	v_fma_f32 v27, -v9, v71, v27
	v_fma_f32 v27, -v11, v72, v27
	v_fma_f32 v27, -v12, v73, v27
	s_waitcnt lgkmcnt(1)
	v_fma_f32 v27, -v15, v74, v27
	ds_read_b128 v[62:65], v5 offset:9952
	ds_read_b128 v[70:73], v5 offset:9968
	v_fma_f32 v27, -v17, v75, v27
	v_fma_f32 v27, -v19, v76, v27
	v_fma_f32 v27, -v20, v77, v27
	s_waitcnt lgkmcnt(2)
	v_fma_f32 v27, -v23, v78, v27
	v_fma_f32 v27, -v25, v79, v27
	s_waitcnt lgkmcnt(1)
	v_pk_mov_b32 v[74:75], v[80:81], v[62:63] op_sel:[1,0]
	v_fma_f32 v27, -v29, v80, v27
	v_pk_mul_f32 v[74:75], v[30:31], v[74:75]
	ds_read_b128 v[78:81], v5 offset:10096
	v_sub_f32_e32 v27, v27, v74
	v_sub_f32_e32 v27, v27, v75
	v_fma_f32 v27, -v43, v63, v27
	v_pk_mul_f32 v[62:63], v[56:57], v[64:65]
	v_mov_b32_e32 v64, v53
	v_sub_f32_e32 v27, v27, v62
	v_sub_f32_e32 v27, v27, v63
	s_waitcnt lgkmcnt(1)
	v_pk_mul_f32 v[62:63], v[50:51], v[70:71]
	v_mov_b32_e32 v65, v54
	v_sub_f32_e32 v27, v27, v62
	ds_read_b64 v[74:75], v5 offset:9984
	v_sub_f32_e32 v27, v27, v63
	v_pk_mul_f32 v[62:63], v[64:65], v[72:73]
	ds_read_b128 v[70:73], v5 offset:10032
	v_sub_f32_e32 v27, v27, v62
	v_sub_f32_e32 v27, v27, v63
	s_waitcnt lgkmcnt(1)
	v_pk_mul_f32 v[62:63], v[74:75], v[60:61]
	ds_read_b128 v[74:77], v5 offset:10048
	s_waitcnt lgkmcnt(1)
	v_fma_f32 v13, -v0, v70, v13
	v_fma_f32 v13, -v2, v71, v13
	v_fma_f32 v13, -v3, v72, v13
	v_fma_f32 v13, -v4, v73, v13
	ds_read_b128 v[70:73], v5 offset:10064
	s_waitcnt lgkmcnt(1)
	v_fma_f32 v13, -v7, v74, v13
	v_fma_f32 v13, -v9, v75, v13
	v_fma_f32 v13, -v11, v76, v13
	v_fma_f32 v13, -v12, v77, v13
	ds_read_b128 v[74:77], v5 offset:10080
	s_waitcnt lgkmcnt(1)
	v_fma_f32 v13, -v15, v70, v13
	v_fma_f32 v13, -v17, v71, v13
	v_fma_f32 v13, -v19, v72, v13
	v_fma_f32 v13, -v20, v73, v13
	s_waitcnt lgkmcnt(0)
	v_fma_f32 v13, -v23, v74, v13
	v_fma_f32 v13, -v25, v75, v13
	v_pk_mov_b32 v[70:71], v[76:77], v[78:79] op_sel:[1,0]
	v_fma_f32 v13, -v29, v76, v13
	v_pk_mul_f32 v[70:71], v[30:31], v[70:71]
	v_mov_b32_e32 v74, v79
	v_sub_f32_e32 v13, v13, v70
	v_sub_f32_e32 v13, v13, v71
	ds_read_b128 v[70:73], v5 offset:10112
	v_mov_b32_e32 v75, v80
	v_pk_mul_f32 v[74:75], v[44:45], v[74:75]
	v_sub_f32_e32 v27, v27, v62
	v_sub_f32_e32 v13, v13, v74
	v_sub_f32_e32 v13, v13, v75
	ds_read_b128 v[74:77], v5 offset:10128
	s_waitcnt lgkmcnt(1)
	v_pk_mov_b32 v[78:79], v[80:81], v[70:71] op_sel:[1,0]
	v_mov_b32_e32 v70, v71
	v_pk_mul_f32 v[78:79], v[46:47], v[78:79]
	v_mov_b32_e32 v71, v72
	v_sub_f32_e32 v5, v13, v78
	v_sub_f32_e32 v5, v5, v79
	v_pk_mul_f32 v[70:71], v[52:53], v[70:71]
	v_sub_f32_e32 v63, v27, v63
	v_sub_f32_e32 v5, v5, v70
	v_sub_f32_e32 v5, v5, v71
	s_waitcnt lgkmcnt(0)
	v_pk_mov_b32 v[70:71], v[72:73], v[74:75] op_sel:[1,0]
	v_mov_b32_e32 v62, v61
	v_pk_mul_f32 v[70:71], v[54:55], v[70:71]
	v_cndmask_b32_e64 v107, 0, 1.0, vcc
	v_sub_f32_e32 v5, v5, v70
	v_sub_f32_e32 v5, v5, v71
	v_mov_b32_e32 v70, v75
	v_mov_b32_e32 v71, v76
	v_pk_mul_f32 v[70:71], v[70:71], v[62:63]
	v_cmp_eq_u32_e32 vcc, 29, v152
	v_sub_f32_e32 v5, v5, v70
	v_sub_f32_e32 v28, v5, v71
	v_cndmask_b32_e64 v106, 0, 1.0, vcc
	v_lshl_add_u32 v5, v1, 2, s3
	ds_read_b128 v[70:73], v5 offset:10176
	ds_read_b128 v[74:77], v5 offset:10192
	ds_read_b128 v[78:81], v5 offset:10208
	ds_read_b128 v[82:85], v5 offset:10224
	ds_read_b128 v[86:89], v5 offset:10240
	ds_read_b128 v[90:93], v5 offset:10256
	ds_read_b128 v[94:97], v5 offset:10272
	ds_read_b128 v[98:101], v5 offset:10320
	ds_read_b128 v[102:105], v5 offset:10336
	s_waitcnt lgkmcnt(8)
	v_mov_b32_e32 v109, v70
	v_cmp_eq_u32_e32 vcc, 31, v152
	v_lshl_add_u64 v[32:33], v[32:33], 0, v[34:35]
	s_waitcnt lgkmcnt(1)
	v_mov_b32_e32 v108, v98
	v_pk_fma_f32 v[106:107], v[0:1], v[108:109], v[106:107] op_sel_hi:[0,1,1] neg_lo:[1,0,0] neg_hi:[1,0,0]
	v_mov_b32_e32 v70, v99
	v_pk_fma_f32 v[70:71], v[2:3], v[70:71], v[106:107] op_sel_hi:[0,1,1] neg_lo:[1,0,0] neg_hi:[1,0,0]
	v_mov_b32_e32 v98, v100
	v_mov_b32_e32 v99, v72
	v_pk_fma_f32 v[26:27], v[26:27], v[98:99], v[70:71] op_sel_hi:[0,1,1] neg_lo:[1,0,0] neg_hi:[1,0,0]
	v_mov_b32_e32 v72, v101
	v_pk_fma_f32 v[26:27], v[4:5], v[72:73], v[26:27] op_sel_hi:[0,1,1] neg_lo:[1,0,0] neg_hi:[1,0,0]
	ds_read_b128 v[70:73], v5 offset:10352
	s_waitcnt lgkmcnt(1)
	v_mov_b32_e32 v98, v102
	v_mov_b32_e32 v99, v74
	v_pk_fma_f32 v[26:27], v[6:7], v[98:99], v[26:27] op_sel:[1,0,0] neg_lo:[1,0,0] neg_hi:[1,0,0]
	v_mov_b32_e32 v74, v103
	v_pk_fma_f32 v[26:27], v[36:37], v[74:75], v[26:27] op_sel_hi:[0,1,1] neg_lo:[1,0,0] neg_hi:[1,0,0]
	v_mov_b32_e32 v36, v104
	v_mov_b32_e32 v37, v76
	ds_read_b128 v[98:101], v5 offset:10368
	v_pk_fma_f32 v[26:27], v[38:39], v[36:37], v[26:27] op_sel_hi:[0,1,1] neg_lo:[1,0,0] neg_hi:[1,0,0]
	v_mov_b32_e32 v76, v105
	v_pk_fma_f32 v[26:27], v[12:13], v[76:77], v[26:27] op_sel_hi:[0,1,1] neg_lo:[1,0,0] neg_hi:[1,0,0]
	s_waitcnt lgkmcnt(1)
	v_mov_b32_e32 v36, v70
	v_mov_b32_e32 v37, v78
	v_pk_fma_f32 v[26:27], v[14:15], v[36:37], v[26:27] op_sel:[1,0,0] neg_lo:[1,0,0] neg_hi:[1,0,0]
	v_mov_b32_e32 v78, v71
	v_pk_fma_f32 v[26:27], v[8:9], v[78:79], v[26:27] op_sel_hi:[0,1,1] neg_lo:[1,0,0] neg_hi:[1,0,0]
	v_mov_b32_e32 v36, v72
	v_mov_b32_e32 v37, v80
	v_pk_fma_f32 v[26:27], v[16:17], v[36:37], v[26:27] op_sel_hi:[0,1,1] neg_lo:[1,0,0] neg_hi:[1,0,0]
	v_mov_b32_e32 v80, v73
	ds_read_b128 v[36:39], v5 offset:10384
	v_pk_fma_f32 v[26:27], v[20:21], v[80:81], v[26:27] op_sel_hi:[0,1,1] neg_lo:[1,0,0] neg_hi:[1,0,0]
	s_waitcnt lgkmcnt(1)
; #define LAS __attribute__((address_space(3)))
; __device__ __forceinline__ void delta_prep_wave(const Params& P, LAS unsigned char* lds, int idx, int wave, int lane) {
;     ...
;     { int loff = hh * 1152;
;       float x[32];
; #pragma unroll
;       for (int i = 0; i < 32; ++i) { float sacc = (i == n) ? 1.f : 0.f;
;           const LAS float* Lb = Lm + loff;
; #pragma unroll
;           for (int j4 = 0; j4 < (i + 3) / 4; ++j4) { const f32x4 l = *(const LAS f32x4*)(Lb + i * 36 + 4 * j4);
; #pragma unroll
;               for (int jj = 0; jj < 4; ++jj) if (4 * j4 + jj < i) sacc -= l[jj] * x[4 * j4 + jj]; }
;           x[i] = sacc;
;           if ((i & 1) == 1) asm volatile("" : "+v"(loff) : "v"(sacc)); }
	v_mov_b32_e32 v70, v98
	v_mov_b32_e32 v71, v82
	v_pk_fma_f32 v[26:27], v[22:23], v[70:71], v[26:27] op_sel:[1,0,0] neg_lo:[1,0,0] neg_hi:[1,0,0]
	v_mov_b32_e32 v82, v99
	v_pk_fma_f32 v[26:27], v[10:11], v[82:83], v[26:27] op_sel_hi:[0,1,1] neg_lo:[1,0,0] neg_hi:[1,0,0]
	v_mov_b32_e32 v70, v100
	v_mov_b32_e32 v71, v84
	v_pk_fma_f32 v[26:27], v[24:25], v[70:71], v[26:27] op_sel_hi:[0,1,1] neg_lo:[1,0,0] neg_hi:[1,0,0]
	v_mov_b32_e32 v84, v101
	v_pk_fma_f32 v[26:27], v[30:31], v[84:85], v[26:27] op_sel_hi:[0,1,1] neg_lo:[1,0,0] neg_hi:[1,0,0]
	s_waitcnt lgkmcnt(0)
	v_mov_b32_e32 v82, v36
	v_mov_b32_e32 v83, v86
	ds_read_b128 v[70:73], v5 offset:10400
	ds_read_b128 v[74:77], v5 offset:10416
	ds_read_b128 v[78:81], v5 offset:10432
	v_pk_fma_f32 v[26:27], v[40:41], v[82:83], v[26:27] op_sel:[1,0,0] neg_lo:[1,0,0] neg_hi:[1,0,0]
	v_mov_b32_e32 v86, v37
	v_pk_fma_f32 v[26:27], v[18:19], v[86:87], v[26:27] op_sel_hi:[0,1,1] neg_lo:[1,0,0] neg_hi:[1,0,0]
	v_mov_b32_e32 v36, v38
	v_mov_b32_e32 v37, v88
	v_pk_fma_f32 v[26:27], v[42:43], v[36:37], v[26:27] op_sel_hi:[0,1,1] neg_lo:[1,0,0] neg_hi:[1,0,0]
	v_mov_b32_e32 v88, v39
	v_pk_fma_f32 v[26:27], v[46:47], v[88:89], v[26:27] op_sel_hi:[0,1,1] neg_lo:[1,0,0] neg_hi:[1,0,0]
	s_waitcnt lgkmcnt(2)
	v_mov_b32_e32 v36, v70
	v_mov_b32_e32 v37, v90
	v_pk_fma_f32 v[26:27], v[48:49], v[36:37], v[26:27] op_sel:[1,0,0] neg_lo:[1,0,0] neg_hi:[1,0,0]
	v_mov_b32_e32 v90, v71
	v_pk_fma_f32 v[26:27], v[66:67], v[90:91], v[26:27] op_sel_hi:[0,1,1] neg_lo:[1,0,0] neg_hi:[1,0,0]
	v_mov_b32_e32 v36, v72
	v_mov_b32_e32 v37, v92
	v_pk_fma_f32 v[26:27], v[68:69], v[36:37], v[26:27] op_sel_hi:[0,1,1] neg_lo:[1,0,0] neg_hi:[1,0,0]
	v_mov_b32_e32 v92, v73
	v_pk_fma_f32 v[26:27], v[54:55], v[92:93], v[26:27] op_sel_hi:[0,1,1] neg_lo:[1,0,0] neg_hi:[1,0,0]
	s_waitcnt lgkmcnt(1)
	v_mov_b32_e32 v36, v74
	v_mov_b32_e32 v37, v94
	v_pk_fma_f32 v[26:27], v[58:59], v[36:37], v[26:27] op_sel:[1,0,0] neg_lo:[1,0,0] neg_hi:[1,0,0]
	v_mov_b32_e32 v94, v75
	v_mov_b32_e32 v6, v61
	v_pk_fma_f32 v[26:27], v[6:7], v[94:95], v[26:27] op_sel_hi:[0,1,1] neg_lo:[1,0,0] neg_hi:[1,0,0]
	v_mov_b32_e32 v36, v76
	v_mov_b32_e32 v37, v96
	v_mov_b32_e32 v6, v63
	v_pk_fma_f32 v[26:27], v[6:7], v[36:37], v[26:27] op_sel_hi:[0,1,1] neg_lo:[1,0,0] neg_hi:[1,0,0]
	v_mov_b32_e32 v96, v77
	v_pk_fma_f32 v[26:27], v[96:97], v[28:29], v[26:27] op_sel_hi:[1,0,1] neg_lo:[1,0,0] neg_hi:[1,0,0]
	v_cndmask_b32_e64 v6, 0, 1.0, vcc
	s_waitcnt lgkmcnt(0)
	v_fma_f32 v79, -v78, v27, v26
	v_mov_b32_e32 v78, v27
	v_lshl_add_u32 v5, v1, 2, s3
	ds_read_b128 v[36:39], v5 offset:10464
	ds_read_b128 v[66:69], v5 offset:10480
	ds_read_b128 v[70:73], v5 offset:10496
	ds_read_b128 v[74:77], v5 offset:10512
	s_mov_b32 s3, 0x1180000
	s_mov_b64 s[4:5], 0x1180000
	v_lshl_add_u64 v[34:35], v[32:33], 0, s[4:5]
	s_waitcnt lgkmcnt(3)
	v_fma_f32 v8, -v0, v36, v21
	v_fma_f32 v8, -v2, v37, v8
	v_fma_f32 v8, -v3, v38, v8
	v_fma_f32 v8, -v4, v39, v8
	s_waitcnt lgkmcnt(2)
	v_fma_f32 v8, -v7, v66, v8
	v_fma_f32 v8, -v9, v67, v8
	v_fma_f32 v8, -v11, v68, v8
	v_fma_f32 v8, -v12, v69, v8
	s_waitcnt lgkmcnt(1)
	v_fma_f32 v8, -v15, v70, v8
	v_fma_f32 v8, -v17, v71, v8
	v_fma_f32 v8, -v19, v72, v8
	v_fma_f32 v8, -v20, v73, v8
	ds_read_b128 v[36:39], v5 offset:10528
	ds_read_b128 v[66:69], v5 offset:10544
	s_waitcnt lgkmcnt(2)
	v_fma_f32 v8, -v23, v74, v8
	v_fma_f32 v8, -v25, v75, v8
	v_fma_f32 v8, -v29, v76, v8
	v_fma_f32 v8, -v30, v77, v8
	s_waitcnt lgkmcnt(1)
	v_fma_f32 v8, -v41, v36, v8
	v_fma_f32 v8, -v43, v37, v8
	v_pk_mul_f32 v[36:37], v[56:57], v[38:39]
	v_mov_b32_e32 v70, v63
	v_sub_f32_e32 v8, v8, v36
	v_sub_f32_e32 v8, v8, v37
	s_waitcnt lgkmcnt(0)
	v_pk_mul_f32 v[36:37], v[50:51], v[66:67]
	v_pk_mul_f32 v[66:67], v[64:65], v[68:69]
	v_sub_f32_e32 v8, v8, v36
	v_sub_f32_e32 v8, v8, v37
	ds_read_b128 v[36:39], v5 offset:10560
	v_sub_f32_e32 v8, v8, v66
	v_sub_f32_e32 v8, v8, v67
	ds_read_b64 v[66:67], v5 offset:10576
	v_mov_b32_e32 v71, v28
	s_waitcnt lgkmcnt(1)
	v_pk_mul_f32 v[36:37], v[60:61], v[36:37]
	v_mov_b32_e32 v72, v79
	v_sub_f32_e32 v8, v8, v36
	v_sub_f32_e32 v8, v8, v37
	v_pk_mul_f32 v[36:37], v[70:71], v[38:39]
	s_waitcnt lgkmcnt(0)
	v_pk_mul_f32 v[66:67], v[66:67], v[78:79]
	v_sub_f32_e32 v8, v8, v36
	v_sub_f32_e32 v8, v8, v37
	ds_read_b128 v[36:39], v5 offset:10608
	v_sub_f32_e32 v8, v8, v66
	v_sub_f32_e32 v73, v8, v67
	ds_read_b128 v[66:69], v5 offset:10624
	s_cselect_b64 s[6:7], -1, 0
	s_waitcnt lgkmcnt(1)
	v_fma_f32 v6, -v0, v36, v6
	v_fma_f32 v6, -v2, v37, v6
	v_fma_f32 v6, -v3, v38, v6
	v_fma_f32 v6, -v4, v39, v6
	ds_read_b128 v[36:39], v5 offset:10640
	s_waitcnt lgkmcnt(1)
	v_fma_f32 v6, -v7, v66, v6
	v_fma_f32 v6, -v9, v67, v6
	v_fma_f32 v6, -v11, v68, v6
	v_fma_f32 v6, -v12, v69, v6
	ds_read_b128 v[66:69], v5 offset:10656
	s_waitcnt lgkmcnt(1)
	v_fma_f32 v6, -v15, v36, v6
	v_fma_f32 v6, -v17, v37, v6
	v_fma_f32 v6, -v19, v38, v6
	v_fma_f32 v6, -v20, v39, v6
	s_waitcnt lgkmcnt(0)
	v_fma_f32 v6, -v23, v66, v6
	ds_read_b128 v[36:39], v5 offset:10672
	v_fma_f32 v6, -v25, v67, v6
	v_fma_f32 v6, -v29, v68, v6
	v_fma_f32 v6, -v30, v69, v6
	ds_read_b128 v[66:69], v5 offset:10688
	s_waitcnt lgkmcnt(1)
	v_fma_f32 v6, -v41, v36, v6
	v_fma_f32 v6, -v43, v37, v6
	v_pk_mul_f32 v[36:37], v[56:57], v[38:39]
	s_cmpk_lg_i32 s78, 0x100
	v_sub_f32_e32 v6, v6, v36
	v_sub_f32_e32 v6, v6, v37
	s_waitcnt lgkmcnt(0)
; #define LAS __attribute__((address_space(3)))
; __device__ __forceinline__ unsigned f2bf(float f) { return pk2(f, f) & 0xffffu; }
; __device__ __forceinline__ int perm16(int e) { return (e & ~12) | ((e >> 1) & 4) | ((e << 1) & 8); }
; __device__ __forceinline__ void delta_prep_wave(const Params& P, LAS unsigned char* lds, int idx, int wave, int lane) {
;     ...
;       for (int i = 0; i < 32; ++i) { float sacc = (i == n) ? 1.f : 0.f;
;           const LAS float* Lb = Lm + loff;
; #pragma unroll
;           for (int j4 = 0; j4 < (i + 3) / 4; ++j4) { const f32x4 l = *(const LAS f32x4*)(Lb + i * 36 + 4 * j4);
; #pragma unroll
;               for (int jj = 0; jj < 4; ++jj) if (4 * j4 + jj < i) sacc -= l[jj] * x[4 * j4 + jj]; }
;           x[i] = sacc;
;           if ((i & 1) == 1) asm volatile("" : "+v"(loff) : "v"(sacc)); }
;       bf16* ti = TINV + ((size_t)bh * 64 + span * 2 + hh) * 1024 + perm16(n);
; #pragma unroll
;       for (int i = 0; i < 32; ++i) ti[i * 32] = (bf16)f2bf(x[i]); }
	v_pk_mul_f32 v[36:37], v[50:51], v[66:67]
	v_pk_mul_f32 v[56:57], v[64:65], v[68:69]
	v_sub_f32_e32 v6, v6, v36
	v_sub_f32_e32 v6, v6, v37
	ds_read_b128 v[36:39], v5 offset:10704
	ds_read_b128 v[64:67], v5 offset:10720
	v_sub_f32_e32 v6, v6, v56
	v_sub_f32_e32 v6, v6, v57
	s_cselect_b64 s[4:5], -1, 0
	s_waitcnt lgkmcnt(1)
	v_pk_mul_f32 v[36:37], v[60:61], v[36:37]
	v_writelane_b32 v238, s4, 21
	v_sub_f32_e32 v5, v6, v36
	v_sub_f32_e32 v5, v5, v37
	v_pk_mul_f32 v[36:37], v[70:71], v[38:39]
	v_cvt_pk_bf16_f32 v6, v0, s0
	v_sub_f32_e32 v5, v5, v36
	v_sub_f32_e32 v5, v5, v37
	s_waitcnt lgkmcnt(0)
	v_mov_b32_e32 v36, v65
	v_mov_b32_e32 v37, v66
	v_fma_f32 v5, -v27, v64, v5
	v_pk_mul_f32 v[36:37], v[36:37], v[72:73]
	v_add_co_u32_e32 v0, vcc, s3, v32
	v_sub_f32_e32 v5, v5, v36
	v_sub_f32_e32 v5, v5, v37
	v_writelane_b32 v238, s5, 22
	v_addc_co_u32_e32 v1, vcc, 0, v33, vcc
	v_and_b32_e32 v100, 31, v166
	v_lshrrev_b32_e32 v101, 5, v166
	v_lshrrev_b32_e32 v102, 6, v167
	v_mul_u32_u24_e32 v102, 0x2800, v102
	v_mul_u32_u24_e32 v103, 0xa00, v101
	v_add_u32_e32 v102, v102, v103
	v_add_u32_e32 v102, 0x1800, v102
	v_and_b32_e32 v103, 0x13, v100
	v_lshrrev_b32_e32 v104, 1, v100
	v_and_b32_e32 v104, 4, v104
	v_lshlrev_b32_e32 v105, 1, v100
	v_and_b32_e32 v105, 8, v105
	v_or3_b32 v103, v103, v104, v105
	v_lshl_add_u32 v106, v103, 1, v102
	v_mul_u32_u24_e32 v107, 0x50, v100
	v_add_u32_e32 v107, v107, v102
	v_lshlrev_b32_e32 v108, 6, v100
	v_lshlrev_b32_e32 v109, 1, v103
	v_sub_u32_e32 v108, v108, v109
	v_mov_b32_e32 v109, 0
	v_lshl_add_u64 v[110:111], v[0:1], 0, v[108:109]
	ds_write_b16 v106, v6
	v_cvt_pk_bf16_f32 v113, v2, s0
	ds_write_b16 v106, v113 offset:80
	v_cvt_pk_bf16_f32 v112, v3, s0
	ds_write_b16 v106, v112 offset:160
	v_cvt_pk_bf16_f32 v113, v4, s0
	ds_write_b16 v106, v113 offset:240
	v_cvt_pk_bf16_f32 v112, v7, s0
	ds_write_b16 v106, v112 offset:320
	v_cvt_pk_bf16_f32 v113, v9, s0
	ds_write_b16 v106, v113 offset:400
	v_cvt_pk_bf16_f32 v112, v11, s0
	ds_write_b16 v106, v112 offset:480
	v_cvt_pk_bf16_f32 v113, v12, s0
	ds_write_b16 v106, v113 offset:560
	v_cvt_pk_bf16_f32 v112, v15, s0
	ds_write_b16 v106, v112 offset:640
	v_cvt_pk_bf16_f32 v113, v17, s0
	ds_write_b16 v106, v113 offset:720
	v_cvt_pk_bf16_f32 v112, v19, s0
	ds_write_b16 v106, v112 offset:800
	v_cvt_pk_bf16_f32 v113, v20, s0
	ds_write_b16 v106, v113 offset:880
	v_cvt_pk_bf16_f32 v112, v23, s0
	ds_write_b16 v106, v112 offset:960
	v_cvt_pk_bf16_f32 v113, v25, s0
	ds_write_b16 v106, v113 offset:1040
	v_cvt_pk_bf16_f32 v112, v29, s0
	ds_write_b16 v106, v112 offset:1120
	v_cvt_pk_bf16_f32 v113, v30, s0
	ds_write_b16 v106, v113 offset:1200
	v_cvt_pk_bf16_f32 v112, v41, s0
	ds_write_b16 v106, v112 offset:1280
	v_cvt_pk_bf16_f32 v113, v43, s0
	ds_write_b16 v106, v113 offset:1360
	v_cvt_pk_bf16_f32 v112, v45, s0
	ds_write_b16 v106, v112 offset:1440
	v_cvt_pk_bf16_f32 v113, v46, s0
	ds_write_b16 v106, v113 offset:1520
	v_cvt_pk_bf16_f32 v112, v49, s0
	ds_write_b16 v106, v112 offset:1600
	v_cvt_pk_bf16_f32 v113, v51, s0
	ds_write_b16 v106, v113 offset:1680
	v_cvt_pk_bf16_f32 v112, v53, s0
	ds_write_b16 v106, v112 offset:1760
	v_cvt_pk_bf16_f32 v113, v54, s0
	ds_write_b16 v106, v113 offset:1840
	v_cvt_pk_bf16_f32 v112, v59, s0
	ds_write_b16 v106, v112 offset:1920
	v_cvt_pk_bf16_f32 v113, v61, s0
	ds_write_b16 v106, v113 offset:2000
	v_cvt_pk_bf16_f32 v112, v63, s0
	ds_write_b16 v106, v112 offset:2080
	v_cvt_pk_bf16_f32 v113, v28, s0
	ds_write_b16 v106, v113 offset:2160
	v_cvt_pk_bf16_f32 v112, v27, s0
	ds_write_b16 v106, v112 offset:2240
	v_cvt_pk_bf16_f32 v113, v79, s0
	ds_write_b16 v106, v113 offset:2320
	v_cvt_pk_bf16_f32 v112, v73, s0
	ds_write_b16 v106, v112 offset:2400
	v_cvt_pk_bf16_f32 v113, v5, s0
	ds_write_b16 v106, v113 offset:2480
	s_waitcnt lgkmcnt(0)
	ds_read_b128 v[116:119], v107
	ds_read_b128 v[120:123], v107 offset:16
	ds_read_b128 v[124:127], v107 offset:32
	ds_read_b128 v[128:131], v107 offset:48
	s_waitcnt lgkmcnt(3)
	global_store_dwordx4 v[110:111], v[116:119], off
	s_waitcnt lgkmcnt(2)
	global_store_dwordx4 v[110:111], v[120:123], off offset:16
	s_waitcnt lgkmcnt(1)
	global_store_dwordx4 v[110:111], v[124:127], off offset:32
	s_waitcnt lgkmcnt(0)
	global_store_dwordx4 v[110:111], v[128:131], off offset:48
	s_waitcnt lgkmcnt(0)
	s_mov_b64 s[4:5], -1
	v_writelane_b32 v238, s6, 18
	s_and_b64 vcc, exec, s[6:7]
	s_barrier
	v_writelane_b32 v238, s7, 19
	s_cmp_eq_u32 s98, 2
	s_cbranch_scc1 .LBB0_1410
	s_cbranch_vccnz .LBB0_1262
	v_readlane_b32 s4, v238, 10
	v_readlane_b32 s5, v238, 11
	s_and_b64 vcc, exec, s[4:5]
	s_cbranch_vccnz .LBB0_1261
	s_mov_b32 s57, 0
	v_mov_b32_e32 v16, 0
	s_add_i32 s3, 0, 0x15880
	v_mov_b32_e32 v75, 0xa0
	v_mov_b32_e32 v150, 0x90
	v_mov_b32_e32 v151, 0x3ecc95a3
	s_movk_i32 s70, 0x830
	s_movk_i32 s71, 0x630
	s_movk_i32 s72, 0x430
	s_movk_i32 s73, 0x230
	s_add_i32 s83, 0, 0x16280
	s_movk_i32 s88, 0x110
	s_add_i32 s89, 0, 0xc800
	s_add_i32 s90, 0, 0x10800
	s_add_i32 s91, 0, 0x14800
	s_add_i32 s94, 0, 0x15000
	s_movk_i32 s95, 0xc00
	s_movk_i32 s96, 0x1000
	v_mov_b32_e32 v152, 0x3c088889
	s_mov_b32 s97, 0xbe99999a
	v_mov_b32_e32 v72, 0x3f317218
	v_mov_b32_e32 v153, 0x7f800000
	v_mov_b32_e32 v154, 0x7fc00000
	v_mov_b32_e32 v155, 0xff800000
	v_mov_b32_e32 v156, 0x8800
	s_mov_b32 s60, s2
	s_branch .LBB0_1111
